# v47 plus: mid-stream full drains removed from gla_passC/ssd_passC load bursts; FoX K-piece norm butterflies on DPP instead of ds_bpermute
# speedup vs baseline: 1.0054x; 1.0054x over previous
.LBB0_165:
	s_cmpk_lt_u32 s85, 0x400
	s_cbranch_scc1 .LBB0_173
	s_add_i32 s2, s85, 0xfffffc00
	s_lshl_b32 s42, s2, 2
	s_lshl_b32 s7, s2, 6
	s_mov_b32 s2, 7
	s_ashr_i32 s3, s2, 31
	s_lshl_b64 s[2:3], s[2:3], 3
	s_add_u32 s2, s0, s2
	s_addc_u32 s3, s1, s3
	s_load_dwordx2 s[2:3], s[2:3], 0x0
	s_mov_b32 s10, 8
	v_mov_b32_e32 v109, v183
	v_mov_b32_e32 v66, v1
	s_waitcnt lgkmcnt(0)
	s_add_u32 s40, s2, s92
	s_addc_u32 s41, s3, s93
	s_ashr_i32 s11, s10, 31
	s_lshl_b64 s[2:3], s[10:11], 3
	s_add_u32 s2, s0, s2
	s_addc_u32 s3, s1, s3
	s_load_dwordx2 s[2:3], s[2:3], 0x0
	s_lshl_b64 s[68:69], s[34:35], 2
	s_mov_b32 s10, 9
	v_mov_b32_e32 v83, v1
	s_waitcnt lgkmcnt(0)
	s_add_u32 s38, s2, s68
	s_addc_u32 s39, s3, s69
	s_ashr_i32 s11, s10, 31
	s_lshl_b64 s[2:3], s[10:11], 3
	s_add_u32 s2, s0, s2
	s_addc_u32 s3, s1, s3
	s_load_dwordx2 s[20:21], s[2:3], 0x0
	v_readlane_b32 s2, v254, 56
	s_waitcnt lgkmcnt(0)
	v_readfirstlane_b32 s11, v109
	v_mov_b32_e32 v85, s2
	v_readlane_b32 s2, v254, 57
	s_ashr_i32 s10, s11, 7
	s_ashr_i32 s6, s11, 6
	v_mov_b32_e32 v87, s2
	s_add_i32 s2, 0, 0x1b000
	v_mov_b32_e32 v189, s2
	v_readlane_b32 s2, v254, 58
	v_lshrrev_b32_e32 v0, 1, v109
	v_and_b32_e32 v0, 16, v0
	v_mov_b32_e32 v187, s2
	s_add_i32 s2, s10, s42
	s_ashr_i32 s3, s2, 31
	s_lshl_b64 s[2:3], s[2:3], 13
	v_readlane_b32 s42, v254, 3
	v_readlane_b32 s43, v254, 4
	s_add_u32 s2, s42, s2
	s_addc_u32 s3, s43, s3
	v_lshl_add_u64 v[2:3], s[2:3], 0, v[0:1]
	v_lshlrev_b32_e32 v0, 7, v109
	v_and_b32_e32 v0, 0xf80, v0
	v_and_b32_e32 v84, 63, v109
	v_lshl_add_u64 v[4:5], v[2:3], 0, v[0:1]
	v_mov_b32_e32 v0, 0x1000
	v_lshl_or_b32 v0, v84, 7, v0
	v_lshl_add_u64 v[2:3], v[2:3], 0, v[0:1]
	v_ashrrev_i32_e32 v160, 8, v109
	s_barrier
	global_load_dwordx4 v[62:65], v[4:5], off
	global_load_dwordx4 v[58:61], v[4:5], off offset:32
	global_load_dwordx4 v[54:57], v[4:5], off offset:64
	global_load_dwordx4 v[50:53], v[4:5], off offset:96
	global_load_dwordx4 v[46:49], v[2:3], off
	global_load_dwordx4 v[42:45], v[2:3], off offset:32
	global_load_dwordx4 v[38:41], v[2:3], off offset:64
	global_load_dwordx4 v[34:37], v[2:3], off offset:96
	v_lshl_add_u32 v30, v160, 5, s7
	v_mov_b64_e32 v[2:3], s[26:27]
	v_mad_i64_i32 v[4:5], s[2:3], v30, s18, v[2:3]
	v_lshlrev_b32_sdwa v0, v180, v109 dst_sel:DWORD dst_unused:UNUSED_PAD src0_sel:DWORD src1_sel:BYTE_0
	v_or_b32_e32 v6, 1, v30
	v_or_b32_e32 v8, 2, v30
	v_lshl_add_u64 v[4:5], v[4:5], 0, v[0:1]
	v_mad_i64_i32 v[6:7], s[2:3], v6, s18, v[2:3]
	v_mad_i64_i32 v[8:9], s[2:3], v8, s18, v[2:3]
	v_lshl_add_u64 v[6:7], v[6:7], 0, v[0:1]
	v_lshl_add_u64 v[8:9], v[8:9], 0, v[0:1]
	flat_load_ushort v185, v[4:5]
	flat_load_ushort v169, v[4:5] offset:512
	flat_load_ushort v168, v[4:5] offset:1024
	flat_load_ushort v161, v[6:7]
	s_nop 0
	flat_load_ushort v156, v[6:7] offset:512
	flat_load_ushort v155, v[6:7] offset:1024
	flat_load_ushort v148, v[8:9]
	flat_load_ushort v144, v[8:9] offset:512
	v_or_b32_e32 v4, 3, v30
	v_mad_i64_i32 v[4:5], s[2:3], v4, s18, v[2:3]
	v_or_b32_e32 v6, 4, v30
	v_or_b32_e32 v10, 5, v30
	v_lshl_add_u64 v[4:5], v[4:5], 0, v[0:1]
	v_mad_i64_i32 v[6:7], s[2:3], v6, s18, v[2:3]
	v_mad_i64_i32 v[10:11], s[2:3], v10, s18, v[2:3]
	v_lshl_add_u64 v[6:7], v[6:7], 0, v[0:1]
	v_lshl_add_u64 v[10:11], v[10:11], 0, v[0:1]
	flat_load_ushort v163, v[8:9] offset:1024
	flat_load_ushort v152, v[4:5]
	flat_load_ushort v151, v[4:5] offset:512
	flat_load_ushort v150, v[4:5] offset:1024
	flat_load_ushort v141, v[6:7]
	flat_load_ushort v139, v[6:7] offset:512
	flat_load_ushort v137, v[6:7] offset:1024
	flat_load_ushort v132, v[10:11]
	v_or_b32_e32 v4, 6, v30
	v_mad_i64_i32 v[4:5], s[2:3], v4, s18, v[2:3]
	v_or_b32_e32 v6, 7, v30
	v_lshl_add_u64 v[4:5], v[4:5], 0, v[0:1]
	v_mad_i64_i32 v[6:7], s[2:3], v6, s18, v[2:3]
	v_lshl_add_u64 v[6:7], v[6:7], 0, v[0:1]
	flat_load_ushort v140, v[10:11] offset:512
	flat_load_ushort v138, v[10:11] offset:1024
	flat_load_ushort v133, v[4:5]
	flat_load_ushort v131, v[4:5] offset:512
	flat_load_ushort v130, v[4:5] offset:1024
	flat_load_ushort v126, v[6:7]
	flat_load_ushort v124, v[6:7] offset:512
	flat_load_ushort v123, v[6:7] offset:1024
	v_or_b32_e32 v4, 8, v30
	v_mad_i64_i32 v[4:5], s[2:3], v4, s18, v[2:3]
	v_or_b32_e32 v6, 9, v30
	v_or_b32_e32 v8, 10, v30
	v_lshl_add_u64 v[4:5], v[4:5], 0, v[0:1]
	v_mad_i64_i32 v[6:7], s[2:3], v6, s18, v[2:3]
	v_mad_i64_i32 v[8:9], s[2:3], v8, s18, v[2:3]
	v_lshl_add_u64 v[6:7], v[6:7], 0, v[0:1]
	v_lshl_add_u64 v[8:9], v[8:9], 0, v[0:1]
	flat_load_ushort v122, v[4:5]
	flat_load_ushort v120, v[4:5] offset:512
	flat_load_ushort v119, v[4:5] offset:1024
	flat_load_ushort v113, v[6:7]
	flat_load_ushort v112, v[6:7] offset:512
	flat_load_ushort v111, v[6:7] offset:1024
	flat_load_ushort v101, v[8:9]
	flat_load_ushort v100, v[8:9] offset:512
	v_or_b32_e32 v4, 11, v30
	v_mad_i64_i32 v[4:5], s[2:3], v4, s18, v[2:3]
	v_or_b32_e32 v6, 12, v30
	v_or_b32_e32 v10, 13, v30
	v_lshl_add_u64 v[4:5], v[4:5], 0, v[0:1]
	v_mad_i64_i32 v[6:7], s[2:3], v6, s18, v[2:3]
	v_mad_i64_i32 v[10:11], s[2:3], v10, s18, v[2:3]
	v_lshl_add_u64 v[6:7], v[6:7], 0, v[0:1]
	v_lshl_add_u64 v[10:11], v[10:11], 0, v[0:1]
	flat_load_ushort v114, v[8:9] offset:1024
	flat_load_ushort v106, v[4:5]
	flat_load_ushort v103, v[4:5] offset:512
	flat_load_ushort v102, v[4:5] offset:1024
	flat_load_ushort v96, v[6:7]
	flat_load_ushort v92, v[6:7] offset:512
	flat_load_ushort v90, v[6:7] offset:1024
	flat_load_ushort v81, v[10:11]
	v_or_b32_e32 v4, 14, v30
	v_mad_i64_i32 v[4:5], s[2:3], v4, s18, v[2:3]
	v_or_b32_e32 v6, 15, v30
	v_lshl_add_u64 v[4:5], v[4:5], 0, v[0:1]
	v_mad_i64_i32 v[6:7], s[2:3], v6, s18, v[2:3]
	v_lshl_add_u64 v[6:7], v[6:7], 0, v[0:1]
	flat_load_ushort v94, v[10:11] offset:512
	flat_load_ushort v91, v[10:11] offset:1024
	flat_load_ushort v86, v[4:5]
	flat_load_ushort v79, v[4:5] offset:512
	flat_load_ushort v78, v[4:5] offset:1024
	flat_load_ushort v77, v[6:7]
	flat_load_ushort v76, v[6:7] offset:512
	flat_load_ushort v75, v[6:7] offset:1024
	v_or_b32_e32 v4, 16, v30
	v_mad_i64_i32 v[4:5], s[2:3], v4, s18, v[2:3]
	v_or_b32_e32 v6, 17, v30
	v_or_b32_e32 v8, 18, v30
	v_lshl_add_u64 v[4:5], v[4:5], 0, v[0:1]
	v_mad_i64_i32 v[6:7], s[2:3], v6, s18, v[2:3]
	v_mad_i64_i32 v[8:9], s[2:3], v8, s18, v[2:3]
	v_lshl_add_u64 v[6:7], v[6:7], 0, v[0:1]
	v_lshl_add_u64 v[8:9], v[8:9], 0, v[0:1]
	flat_load_ushort v74, v[4:5]
	flat_load_ushort v73, v[4:5] offset:512
	flat_load_ushort v72, v[4:5] offset:1024
	flat_load_ushort v71, v[6:7]
	flat_load_ushort v70, v[6:7] offset:512
	flat_load_ushort v69, v[6:7] offset:1024
	flat_load_ushort v68, v[8:9]
	flat_load_ushort v67, v[8:9] offset:512
	v_or_b32_e32 v4, 19, v30
	v_mad_i64_i32 v[4:5], s[2:3], v4, s18, v[2:3]
	v_lshl_add_u64 v[10:11], v[4:5], 0, v[0:1]
	v_or_b32_e32 v4, 20, v30
	v_mad_i64_i32 v[4:5], s[2:3], v4, s18, v[2:3]
	v_lshl_add_u64 v[12:13], v[4:5], 0, v[0:1]
	v_or_b32_e32 v4, 21, v30
	v_and_b32_e32 v89, 31, v109
	v_mad_i64_i32 v[4:5], s[2:3], v4, s18, v[2:3]
	v_bfe_u32 v93, v109, 5, 1
	v_or_b32_e32 v16, s7, v89
	v_lshl_add_u64 v[14:15], v[4:5], 0, v[0:1]
	v_mad_i64_i32 v[4:5], s[2:3], v16, s18, v[2:3]
	v_lshlrev_b32_e32 v82, 4, v93
	v_lshl_add_u64 v[4:5], v[4:5], 0, v[82:83]
	s_movk_i32 s42, 0x1000
	v_add_co_u32_e32 v4, vcc, s42, v4
	v_lshl_or_b32 v190, s6, 5, v89
	s_nop 0
	v_addc_co_u32_e32 v5, vcc, 0, v5, vcc
	flat_load_dwordx4 v[4:7], v[4:5] offset:3072
	v_lshl_add_u32 v18, v93, 11, v190
	v_or_b32_e32 v16, 32, v16
	v_ashrrev_i32_e32 v19, 31, v18
	v_mad_i64_i32 v[16:17], s[2:3], v16, s18, v[2:3]
	v_lshl_add_u64 v[20:21], v[18:19], 2, s[40:41]
	v_add_u32_e32 v22, 0x400, v18
	v_add_u32_e32 v24, 0x500, v18
	v_add_u32_e32 v26, 0x600, v18
	v_add_u32_e32 v18, 0x700, v18
	v_lshl_add_u64 v[16:17], v[16:17], 0, v[82:83]
	v_ashrrev_i32_e32 v25, 31, v24
	v_ashrrev_i32_e32 v19, 31, v18
	v_add_co_u32_e32 v16, vcc, s42, v16
	v_ashrrev_i32_e32 v23, 31, v22
	v_lshl_add_u64 v[24:25], v[24:25], 2, s[40:41]
	v_ashrrev_i32_e32 v27, 31, v26
	v_lshl_add_u64 v[18:19], v[18:19], 2, s[40:41]
	v_ashrrev_i32_e32 v191, 31, v190
	v_addc_co_u32_e32 v17, vcc, 0, v17, vcc
	v_lshl_add_u64 v[22:23], v[22:23], 2, s[40:41]
	v_lshl_add_u64 v[26:27], v[26:27], 2, s[40:41]
	global_load_dword v32, v[20:21], off
	global_load_dword v33, v[20:21], off offset:1024
	global_load_dword v80, v[20:21], off offset:2048
	global_load_dword v83, v[20:21], off offset:3072
	global_load_dword v88, v[22:23], off
	s_nop 0
	global_load_dword v24, v[24:25], off
	s_nop 0
	global_load_dword v25, v[26:27], off
	global_load_dword v95, v[18:19], off
	s_nop 0
	flat_load_dwordx4 v[18:21], v[16:17] offset:3072
	flat_load_ushort v186, v[8:9] offset:1024
	flat_load_ushort v184, v[10:11]
	flat_load_ushort v167, v[10:11] offset:512
	flat_load_ushort v166, v[10:11] offset:1024
	flat_load_ushort v162, v[12:13]
	flat_load_ushort v159, v[12:13] offset:512
	flat_load_ushort v157, v[12:13] offset:1024
	flat_load_ushort v149, v[14:15]
	v_lshl_add_u64 v[8:9], v[190:191], 2, s[38:39]
	global_load_dword v188, v[8:9], off
	v_or_b32_e32 v10, 22, v30
	v_mad_i64_i32 v[8:9], s[2:3], v10, s18, v[2:3]
	v_or_b32_e32 v10, 23, v30
	v_lshl_add_u64 v[8:9], v[8:9], 0, v[0:1]
	v_mad_i64_i32 v[10:11], s[2:3], v10, s18, v[2:3]
	v_lshl_add_u64 v[10:11], v[10:11], 0, v[0:1]
	flat_load_ushort v165, v[14:15] offset:512
	flat_load_ushort v164, v[14:15] offset:1024
	flat_load_ushort v158, v[8:9]
	flat_load_ushort v154, v[8:9] offset:512
	flat_load_ushort v153, v[8:9] offset:1024
	flat_load_ushort v147, v[10:11]
	flat_load_ushort v143, v[10:11] offset:512
	flat_load_ushort v142, v[10:11] offset:1024
	v_or_b32_e32 v8, 24, v30
	v_mad_i64_i32 v[8:9], s[2:3], v8, s18, v[2:3]
	v_or_b32_e32 v10, 25, v30
	v_or_b32_e32 v12, 26, v30
	v_lshl_add_u64 v[8:9], v[8:9], 0, v[0:1]
	v_mad_i64_i32 v[10:11], s[2:3], v10, s18, v[2:3]
	v_mad_i64_i32 v[12:13], s[2:3], v12, s18, v[2:3]
	v_lshl_add_u64 v[10:11], v[10:11], 0, v[0:1]
	v_lshl_add_u64 v[12:13], v[12:13], 0, v[0:1]
	flat_load_ushort v136, v[8:9]
	flat_load_ushort v135, v[8:9] offset:512
	flat_load_ushort v134, v[8:9] offset:1024
	flat_load_ushort v129, v[10:11]
	flat_load_ushort v128, v[10:11] offset:512
	flat_load_ushort v127, v[10:11] offset:1024
	flat_load_ushort v121, v[12:13]
	flat_load_ushort v117, v[12:13] offset:512
	v_or_b32_e32 v8, 27, v30
	v_mad_i64_i32 v[8:9], s[2:3], v8, s18, v[2:3]
	v_or_b32_e32 v10, 28, v30
	v_or_b32_e32 v14, 29, v30
	v_lshl_add_u64 v[8:9], v[8:9], 0, v[0:1]
	v_mad_i64_i32 v[10:11], s[2:3], v10, s18, v[2:3]
	v_mad_i64_i32 v[14:15], s[2:3], v14, s18, v[2:3]
	v_lshl_add_u64 v[10:11], v[10:11], 0, v[0:1]
	v_lshl_add_u64 v[26:27], v[14:15], 0, v[0:1]
	flat_load_ushort v125, v[12:13] offset:1024
	flat_load_ushort v118, v[8:9]
	flat_load_ushort v116, v[8:9] offset:512
	flat_load_ushort v115, v[8:9] offset:1024
	flat_load_ushort v110, v[10:11]
	flat_load_ushort v107, v[10:11] offset:512
	flat_load_ushort v104, v[10:11] offset:1024
	flat_load_ushort v98, v[26:27]
	v_or_b32_e32 v8, 30, v30
	v_mad_i64_i32 v[8:9], s[2:3], v8, s18, v[2:3]
	v_lshl_add_u64 v[28:29], v[8:9], 0, v[0:1]
	v_or_b32_e32 v8, 31, v30
	v_mad_i64_i32 v[2:3], s[2:3], v8, s18, v[2:3]
	v_lshl_add_u64 v[30:31], v[2:3], 0, v[0:1]
	v_lshlrev_b32_e32 v190, 1, v190
	v_mul_u32_u24_e32 v191, 0x840, v93
	v_add3_u32 v192, v189, v190, v191
	s_mov_b32 s2, 0x3d800000
	s_waitcnt vmcnt(0)
	v_cvt_pk_bf16_f32 v22, v32, v33
	v_cvt_pk_bf16_f32 v23, v80, v83
	v_cvt_pk_bf16_f32 v24, v88, v24
	v_cvt_pk_bf16_f32 v25, v25, v95
	flat_load_ushort v108, v[26:27] offset:512
	flat_load_ushort v105, v[26:27] offset:1024
	flat_load_ushort v99, v[28:29]
	flat_load_ushort v97, v[28:29] offset:512
	flat_load_ushort v95, v[28:29] offset:1024
	flat_load_ushort v88, v[30:31]
	flat_load_ushort v83, v[30:31] offset:512
	flat_load_ushort v80, v[30:31] offset:1024
	s_waitcnt lgkmcnt(0)
	v_mfma_f32_32x32x16_bf16 v[2:17], v[4:7], v[22:25], 0
	v_mfma_f32_32x32x16_bf16 v[18:33], v[18:21], v[22:25], 0
	s_nop 10
	v_add_f32_e32 v2, v188, v2
	v_cvt_pk_bf16_f32 v2, v2, s0
	ds_write_b16 v192, v2
	v_add_f32_e32 v2, v188, v18
	v_cvt_pk_bf16_f32 v2, v2, s0
	v_add3_u32 v18, v189, v191, v190
	ds_write_b16 v18, v2 offset:16896
	v_add_f32_e32 v2, v188, v3
	v_cvt_pk_bf16_f32 v2, v2, s0
	ds_write_b16 v192, v2 offset:528
	v_add_f32_e32 v2, v188, v19
	v_cvt_pk_bf16_f32 v2, v2, s0
	ds_write_b16 v18, v2 offset:17424
	v_add_f32_e32 v2, v188, v4
	v_cvt_pk_bf16_f32 v2, v2, s0
	ds_write_b16 v192, v2 offset:1056
	v_add_f32_e32 v2, v188, v20
	v_cvt_pk_bf16_f32 v2, v2, s0
	ds_write_b16 v18, v2 offset:17952
	v_add_f32_e32 v2, v188, v5
	v_cvt_pk_bf16_f32 v2, v2, s0
	ds_write_b16 v192, v2 offset:1584
	v_add_f32_e32 v2, v188, v21
	v_cvt_pk_bf16_f32 v2, v2, s0
	ds_write_b16 v18, v2 offset:18480
	v_add_f32_e32 v2, v188, v6
	v_cvt_pk_bf16_f32 v2, v2, s0
	ds_write_b16 v192, v2 offset:4224
	v_add_f32_e32 v2, v188, v22
	v_cvt_pk_bf16_f32 v2, v2, s0
	ds_write_b16 v18, v2 offset:21120
	v_add_f32_e32 v2, v188, v7
	v_cvt_pk_bf16_f32 v2, v2, s0
	ds_write_b16 v192, v2 offset:4752
	v_add_f32_e32 v2, v188, v23
	v_cvt_pk_bf16_f32 v2, v2, s0
	ds_write_b16 v18, v2 offset:21648
	v_add_f32_e32 v2, v188, v8
	v_cvt_pk_bf16_f32 v2, v2, s0
	ds_write_b16 v192, v2 offset:5280
	v_add_f32_e32 v2, v188, v24
	v_cvt_pk_bf16_f32 v2, v2, s0
	ds_write_b16 v18, v2 offset:22176
	v_add_f32_e32 v2, v188, v9
	v_cvt_pk_bf16_f32 v2, v2, s0
	ds_write_b16 v192, v2 offset:5808
	v_add_f32_e32 v2, v188, v25
	v_cvt_pk_bf16_f32 v2, v2, s0
	ds_write_b16 v18, v2 offset:22704
	v_add_f32_e32 v2, v188, v10
	v_cvt_pk_bf16_f32 v2, v2, s0
	ds_write_b16 v192, v2 offset:8448
	v_add_f32_e32 v2, v188, v26
	v_cvt_pk_bf16_f32 v2, v2, s0
	ds_write_b16 v18, v2 offset:25344
	v_add_f32_e32 v2, v188, v11
	v_cvt_pk_bf16_f32 v2, v2, s0
	ds_write_b16 v192, v2 offset:8976
	v_add_f32_e32 v2, v188, v27
	v_cvt_pk_bf16_f32 v2, v2, s0
	ds_write_b16 v18, v2 offset:25872
	v_add_f32_e32 v2, v188, v12
	v_cvt_pk_bf16_f32 v2, v2, s0
	ds_write_b16 v192, v2 offset:9504
	v_add_f32_e32 v2, v188, v28
	v_cvt_pk_bf16_f32 v2, v2, s0
	ds_write_b16 v18, v2 offset:26400
	v_add_f32_e32 v2, v188, v13
	v_cvt_pk_bf16_f32 v2, v2, s0
	ds_write_b16 v192, v2 offset:10032
	v_add_f32_e32 v2, v188, v29
	v_cvt_pk_bf16_f32 v2, v2, s0
	ds_write_b16 v18, v2 offset:26928
	v_add_f32_e32 v2, v188, v14
	v_cvt_pk_bf16_f32 v2, v2, s0
	ds_write_b16 v192, v2 offset:12672
	v_add_f32_e32 v2, v188, v30
	v_cvt_pk_bf16_f32 v2, v2, s0
	ds_write_b16 v18, v2 offset:29568
	v_add_f32_e32 v2, v188, v15
	v_cvt_pk_bf16_f32 v2, v2, s0
	ds_write_b16 v192, v2 offset:13200
	v_add_f32_e32 v2, v188, v31
	v_cvt_pk_bf16_f32 v2, v2, s0
	ds_write_b16 v18, v2 offset:30096
	v_add_f32_e32 v2, v188, v16
	v_cvt_pk_bf16_f32 v2, v2, s0
	ds_write_b16 v192, v2 offset:13728
	v_add_f32_e32 v2, v188, v32
	v_cvt_pk_bf16_f32 v2, v2, s0
	ds_write_b16 v18, v2 offset:30624
	v_add_f32_e32 v2, v188, v17
	v_cvt_pk_bf16_f32 v2, v2, s0
	ds_write_b16 v192, v2 offset:14256
	v_add_f32_e32 v2, v188, v33
	v_mul_i32_i24_e32 v188, 0x4200, v160
	v_cvt_pk_bf16_f32 v2, v2, s0
	v_add3_u32 v24, v189, v0, v188
	ds_write_b16 v18, v2 offset:31152
	s_waitcnt lgkmcnt(0)
	s_barrier
	ds_read_u16 v2, v24
	ds_read_u16 v3, v24 offset:528
	ds_read_u16 v4, v24 offset:1056
	ds_read_u16 v5, v24 offset:1584
	ds_read_u16 v6, v24 offset:2112
	ds_read_u16 v7, v24 offset:2640
	ds_read_u16 v8, v24 offset:3168
	ds_read_u16 v9, v24 offset:3696
	s_waitcnt lgkmcnt(0)
	v_lshlrev_b32_e32 v2, 16, v2
	v_mul_f32_e64 v10, |v2|, s19
	v_exp_f32_e32 v10, v10
	v_lshlrev_b32_e32 v3, 16, v3
	v_mul_f32_e64 v12, |v3|, s19
	v_exp_f32_e32 v12, v12
	v_add_f32_e32 v10, 1.0, v10
	v_cmp_gt_f32_e32 vcc, s96, v10
	v_max_f32_e32 v2, v2, v2
	v_min_f32_e32 v2, 0, v2
	v_cndmask_b32_e64 v11, 0, 32, vcc
	v_ldexp_f32 v10, v10, v11
	v_log_f32_e32 v10, v10
	v_lshlrev_b32_e32 v4, 16, v4
	v_max_f32_e32 v3, v3, v3
	v_min_f32_e32 v3, 0, v3
	v_mul_f32_e32 v11, 0x3f317217, v10
	v_fma_f32 v11, v10, s97, -v11
	v_fmac_f32_e32 v11, 0x3377d1cf, v10
	v_fmac_f32_e32 v11, 0x3f317217, v10
	v_cmp_lt_f32_e64 s[38:39], |v10|, s15
	v_lshlrev_b32_e32 v5, 16, v5
	v_lshlrev_b32_e32 v6, 16, v6
	v_cndmask_b32_e64 v10, v10, v11, s[38:39]
	v_cndmask_b32_e32 v11, 0, v179, vcc
	v_sub_f32_e32 v10, v10, v11
	v_add_f32_e32 v11, 1.0, v12
	v_cmp_gt_f32_e32 vcc, s96, v11
	v_sub_f32_e32 v2, v2, v10
	v_lshlrev_b32_e32 v7, 16, v7
	v_cndmask_b32_e64 v12, 0, 32, vcc
	v_ldexp_f32 v11, v11, v12
	v_log_f32_e32 v11, v11
	v_mul_f32_e64 v12, |v4|, s19
	v_exp_f32_e32 v12, v12
	v_max_f32_e32 v4, v4, v4
	v_mul_f32_e32 v10, 0x3f317217, v11
	v_fma_f32 v10, v11, s97, -v10
	v_fmac_f32_e32 v10, 0x3377d1cf, v11
	v_fmac_f32_e32 v10, 0x3f317217, v11
	v_cmp_lt_f32_e64 s[38:39], |v11|, s15
	v_min_f32_e32 v4, 0, v4
	v_lshlrev_b32_e32 v8, 16, v8
	v_cndmask_b32_e64 v10, v11, v10, s[38:39]
	v_cndmask_b32_e32 v11, 0, v179, vcc
	v_sub_f32_e32 v10, v10, v11
	v_sub_f32_e32 v3, v3, v10
	v_add_f32_e32 v10, 1.0, v12
	v_cmp_gt_f32_e32 vcc, s96, v10
	v_mul_f32_e64 v12, |v5|, s19
	v_exp_f32_e32 v12, v12
	v_cndmask_b32_e64 v11, 0, 32, vcc
	v_ldexp_f32 v10, v10, v11
	v_log_f32_e32 v10, v10
	v_max_f32_e32 v5, v5, v5
	v_min_f32_e32 v5, 0, v5
	v_lshlrev_b32_e32 v9, 16, v9
	v_mul_f32_e32 v11, 0x3f317217, v10
	v_fma_f32 v11, v10, s97, -v11
	v_fmac_f32_e32 v11, 0x3377d1cf, v10
	v_fmac_f32_e32 v11, 0x3f317217, v10
	v_cmp_lt_f32_e64 s[38:39], |v10|, s15
	v_fma_f32 v2, v2, s2, 0
	v_fmamk_f32 v3, v3, 0x3d800000, v2
	v_cndmask_b32_e64 v10, v10, v11, s[38:39]
	v_cndmask_b32_e32 v11, 0, v179, vcc
	v_sub_f32_e32 v10, v10, v11
	v_add_f32_e32 v11, 1.0, v12
	v_cmp_gt_f32_e32 vcc, s96, v11
	v_sub_f32_e32 v4, v4, v10
	v_fmamk_f32 v4, v4, 0x3d800000, v3
	v_cndmask_b32_e64 v12, 0, 32, vcc
	v_ldexp_f32 v11, v11, v12
	v_log_f32_e32 v11, v11
	v_mul_f32_e64 v12, |v6|, s19
	v_exp_f32_e32 v12, v12
	v_max_f32_e32 v6, v6, v6
	v_mul_f32_e32 v10, 0x3f317217, v11
	v_fma_f32 v10, v11, s97, -v10
	v_fmac_f32_e32 v10, 0x3377d1cf, v11
	v_fmac_f32_e32 v10, 0x3f317217, v11
	v_cmp_lt_f32_e64 s[38:39], |v11|, s15
	v_min_f32_e32 v6, 0, v6
	s_movk_i32 s2, 0xff
	v_cndmask_b32_e64 v10, v11, v10, s[38:39]
	v_cndmask_b32_e32 v11, 0, v179, vcc
	v_sub_f32_e32 v10, v10, v11
	v_sub_f32_e32 v5, v5, v10
	v_add_f32_e32 v10, 1.0, v12
	v_cmp_gt_f32_e32 vcc, s96, v10
	v_mul_f32_e64 v12, |v7|, s19
	v_exp_f32_e32 v12, v12
	v_cndmask_b32_e64 v11, 0, 32, vcc
	v_ldexp_f32 v10, v10, v11
	v_log_f32_e32 v10, v10
	v_max_f32_e32 v7, v7, v7
	v_min_f32_e32 v7, 0, v7
	v_fmamk_f32 v5, v5, 0x3d800000, v4
	v_mul_f32_e32 v11, 0x3f317217, v10
	v_fma_f32 v11, v10, s97, -v11
	v_fmac_f32_e32 v11, 0x3377d1cf, v10
	v_fmac_f32_e32 v11, 0x3f317217, v10
	v_cmp_lt_f32_e64 s[38:39], |v10|, s15
	s_nop 1
	v_cndmask_b32_e64 v10, v10, v11, s[38:39]
	v_cndmask_b32_e32 v11, 0, v179, vcc
	v_sub_f32_e32 v10, v10, v11
	v_add_f32_e32 v11, 1.0, v12
	v_cmp_gt_f32_e32 vcc, s96, v11
	v_sub_f32_e32 v6, v6, v10
	v_fmamk_f32 v6, v6, 0x3d800000, v5
	v_cndmask_b32_e64 v12, 0, 32, vcc
	v_ldexp_f32 v11, v11, v12
	v_log_f32_e32 v11, v11
	v_mul_f32_e64 v12, |v8|, s19
	v_exp_f32_e32 v12, v12
	v_max_f32_e32 v8, v8, v8
	v_mul_f32_e32 v10, 0x3f317217, v11
	v_fma_f32 v10, v11, s97, -v10
	v_fmac_f32_e32 v10, 0x3377d1cf, v11
	v_fmac_f32_e32 v10, 0x3f317217, v11
	v_cmp_lt_f32_e64 s[38:39], |v11|, s15
	v_min_f32_e32 v8, 0, v8
	s_nop 0
	v_cndmask_b32_e64 v10, v11, v10, s[38:39]
	v_cndmask_b32_e32 v11, 0, v179, vcc
	v_sub_f32_e32 v10, v10, v11
	v_sub_f32_e32 v7, v7, v10
	v_add_f32_e32 v10, 1.0, v12
	v_cmp_gt_f32_e32 vcc, s96, v10
	v_mul_f32_e64 v12, |v9|, s19
	v_exp_f32_e32 v12, v12
	v_cndmask_b32_e64 v11, 0, 32, vcc
	v_ldexp_f32 v10, v10, v11
	v_log_f32_e32 v10, v10
	v_max_f32_e32 v9, v9, v9
	v_min_f32_e32 v9, 0, v9
	v_fmamk_f32 v7, v7, 0x3d800000, v6
	v_mul_f32_e32 v11, 0x3f317217, v10
	v_fma_f32 v11, v10, s97, -v11
	v_fmac_f32_e32 v11, 0x3377d1cf, v10
	v_fmac_f32_e32 v11, 0x3f317217, v10
	v_cmp_lt_f32_e64 s[38:39], |v10|, s15
	s_nop 1
	v_cndmask_b32_e64 v10, v10, v11, s[38:39]
	v_cndmask_b32_e32 v11, 0, v179, vcc
	v_sub_f32_e32 v10, v10, v11
	v_add_f32_e32 v11, 1.0, v12
	v_cmp_gt_f32_e32 vcc, s96, v11
	v_sub_f32_e32 v8, v8, v10
	v_fmamk_f32 v8, v8, 0x3d800000, v7
	v_cndmask_b32_e64 v12, 0, 32, vcc
	v_ldexp_f32 v11, v11, v12
	v_log_f32_e32 v11, v11
	ds_read_u16 v12, v24 offset:4224
	ds_read_u16 v13, v24 offset:4752
	ds_read_u16 v14, v24 offset:5280
	ds_read_u16 v15, v24 offset:5808
	ds_read_u16 v16, v24 offset:6336
	ds_read_u16 v17, v24 offset:6864
	ds_read_u16 v18, v24 offset:7392
	ds_read_u16 v19, v24 offset:7920
	s_waitcnt lgkmcnt(0)
	v_lshlrev_b32_e32 v12, 16, v12
	v_mul_f32_e64 v20, |v12|, s19
	v_mul_f32_e32 v10, 0x3f317217, v11
	v_fma_f32 v10, v11, s97, -v10
	v_fmac_f32_e32 v10, 0x3377d1cf, v11
	v_exp_f32_e32 v20, v20
	v_fmac_f32_e32 v10, 0x3f317217, v11
	v_cmp_lt_f32_e64 s[38:39], |v11|, s15
	v_lshlrev_b32_e32 v13, 16, v13
	v_lshlrev_b32_e32 v14, 16, v14
	v_cndmask_b32_e64 v10, v11, v10, s[38:39]
	v_cndmask_b32_e32 v11, 0, v179, vcc
	v_sub_f32_e32 v10, v10, v11
	v_sub_f32_e32 v9, v9, v10
	v_add_f32_e32 v10, 1.0, v20
	v_cmp_gt_f32_e32 vcc, s96, v10
	v_mul_f32_e64 v20, |v13|, s19
	v_exp_f32_e32 v20, v20
	v_cndmask_b32_e64 v11, 0, 32, vcc
	v_ldexp_f32 v10, v10, v11
	v_log_f32_e32 v10, v10
	v_max_f32_e32 v11, v12, v12
	v_min_f32_e32 v11, 0, v11
	v_lshlrev_b32_e32 v15, 16, v15
	v_mul_f32_e32 v12, 0x3f317217, v10
	v_fma_f32 v12, v10, s97, -v12
	v_fmac_f32_e32 v12, 0x3377d1cf, v10
	v_fmac_f32_e32 v12, 0x3f317217, v10
	v_cmp_lt_f32_e64 s[38:39], |v10|, s15
	v_lshlrev_b32_e32 v16, 16, v16
	v_lshlrev_b32_e32 v17, 16, v17
	v_cndmask_b32_e64 v10, v10, v12, s[38:39]
	v_cndmask_b32_e32 v12, 0, v179, vcc
	v_sub_f32_e32 v10, v10, v12
	v_add_f32_e32 v12, 1.0, v20
	v_cmp_gt_f32_e32 vcc, s96, v12
	v_sub_f32_e32 v10, v11, v10
	v_max_f32_e32 v11, v13, v13
	v_cndmask_b32_e64 v20, 0, 32, vcc
	v_ldexp_f32 v12, v12, v20
	v_log_f32_e32 v12, v12
	v_mul_f32_e64 v20, |v14|, s19
	v_exp_f32_e32 v20, v20
	v_min_f32_e32 v11, 0, v11
	v_mul_f32_e32 v13, 0x3f317217, v12
	v_fma_f32 v13, v12, s97, -v13
	v_fmac_f32_e32 v13, 0x3377d1cf, v12
	v_fmac_f32_e32 v13, 0x3f317217, v12
	v_cmp_lt_f32_e64 s[38:39], |v12|, s15
	v_lshlrev_b32_e32 v18, 16, v18
	v_lshlrev_b32_e32 v19, 16, v19
	v_cndmask_b32_e64 v12, v12, v13, s[38:39]
	v_cndmask_b32_e32 v13, 0, v179, vcc
	v_sub_f32_e32 v12, v12, v13
	v_sub_f32_e32 v11, v11, v12
	v_add_f32_e32 v12, 1.0, v20
	v_cmp_gt_f32_e32 vcc, s96, v12
	v_mul_f32_e64 v20, |v15|, s19
	v_exp_f32_e32 v20, v20
	v_cndmask_b32_e64 v13, 0, 32, vcc
	v_ldexp_f32 v12, v12, v13
	v_log_f32_e32 v12, v12
	v_max_f32_e32 v13, v14, v14
	v_min_f32_e32 v13, 0, v13
	v_fmamk_f32 v9, v9, 0x3d800000, v8
	v_mul_f32_e32 v14, 0x3f317217, v12
	v_fma_f32 v14, v12, s97, -v14
	v_fmac_f32_e32 v14, 0x3377d1cf, v12
	v_fmac_f32_e32 v14, 0x3f317217, v12
	v_cmp_lt_f32_e64 s[38:39], |v12|, s15
	v_fmamk_f32 v10, v10, 0x3d800000, v9
	v_fmamk_f32 v11, v11, 0x3d800000, v10
	v_cndmask_b32_e64 v12, v12, v14, s[38:39]
	v_cndmask_b32_e32 v14, 0, v179, vcc
	v_sub_f32_e32 v12, v12, v14
	v_add_f32_e32 v14, 1.0, v20
	v_cmp_gt_f32_e32 vcc, s96, v14
	v_sub_f32_e32 v12, v13, v12
	v_max_f32_e32 v13, v15, v15
	v_cndmask_b32_e64 v20, 0, 32, vcc
	v_ldexp_f32 v14, v14, v20
	v_log_f32_e32 v14, v14
	v_mul_f32_e64 v20, |v16|, s19
	v_exp_f32_e32 v20, v20
	v_min_f32_e32 v13, 0, v13
	v_mul_f32_e32 v15, 0x3f317217, v14
	v_fma_f32 v15, v14, s97, -v15
	v_fmac_f32_e32 v15, 0x3377d1cf, v14
	v_fmac_f32_e32 v15, 0x3f317217, v14
	v_cmp_lt_f32_e64 s[38:39], |v14|, s15
	v_fmamk_f32 v12, v12, 0x3d800000, v11
	s_nop 0
	v_cndmask_b32_e64 v14, v14, v15, s[38:39]
	v_cndmask_b32_e32 v15, 0, v179, vcc
	v_sub_f32_e32 v14, v14, v15
	v_sub_f32_e32 v13, v13, v14
	v_add_f32_e32 v14, 1.0, v20
	v_cmp_gt_f32_e32 vcc, s96, v14
	v_mul_f32_e64 v20, |v17|, s19
	v_exp_f32_e32 v20, v20
	v_cndmask_b32_e64 v15, 0, 32, vcc
	v_ldexp_f32 v14, v14, v15
	v_log_f32_e32 v14, v14
	v_max_f32_e32 v15, v16, v16
	v_min_f32_e32 v15, 0, v15
	v_fmamk_f32 v13, v13, 0x3d800000, v12
	v_mul_f32_e32 v16, 0x3f317217, v14
	v_fma_f32 v16, v14, s97, -v16
	v_fmac_f32_e32 v16, 0x3377d1cf, v14
	v_fmac_f32_e32 v16, 0x3f317217, v14
	v_cmp_lt_f32_e64 s[38:39], |v14|, s15
	s_nop 1
	v_cndmask_b32_e64 v14, v14, v16, s[38:39]
	v_cndmask_b32_e32 v16, 0, v179, vcc
	v_sub_f32_e32 v14, v14, v16
	v_add_f32_e32 v16, 1.0, v20
	v_cmp_gt_f32_e32 vcc, s96, v16
	v_sub_f32_e32 v14, v15, v14
	v_max_f32_e32 v15, v17, v17
	v_cndmask_b32_e64 v20, 0, 32, vcc
	v_ldexp_f32 v16, v16, v20
	v_log_f32_e32 v16, v16
	v_mul_f32_e64 v20, |v18|, s19
	v_exp_f32_e32 v20, v20
	v_min_f32_e32 v15, 0, v15
	v_mul_f32_e32 v17, 0x3f317217, v16
	v_fma_f32 v17, v16, s97, -v17
	v_fmac_f32_e32 v17, 0x3377d1cf, v16
	v_fmac_f32_e32 v17, 0x3f317217, v16
	v_cmp_lt_f32_e64 s[38:39], |v16|, s15
	v_fmamk_f32 v14, v14, 0x3d800000, v13
	s_nop 0
	v_cndmask_b32_e64 v16, v16, v17, s[38:39]
	v_cndmask_b32_e32 v17, 0, v179, vcc
	v_sub_f32_e32 v16, v16, v17
	v_sub_f32_e32 v15, v15, v16
	v_add_f32_e32 v16, 1.0, v20
	v_cmp_gt_f32_e32 vcc, s96, v16
	v_mul_f32_e64 v20, |v19|, s19
	v_exp_f32_e32 v20, v20
	v_cndmask_b32_e64 v17, 0, 32, vcc
	v_ldexp_f32 v16, v16, v17
	v_log_f32_e32 v16, v16
	v_max_f32_e32 v17, v18, v18
	v_min_f32_e32 v17, 0, v17
	v_fmamk_f32 v15, v15, 0x3d800000, v14
	v_mul_f32_e32 v18, 0x3f317217, v16
	v_fma_f32 v18, v16, s97, -v18
	v_fmac_f32_e32 v18, 0x3377d1cf, v16
	v_fmac_f32_e32 v18, 0x3f317217, v16
	v_cmp_lt_f32_e64 s[38:39], |v16|, s15
	s_nop 1
	v_cndmask_b32_e64 v16, v16, v18, s[38:39]
	v_cndmask_b32_e32 v18, 0, v179, vcc
	v_sub_f32_e32 v16, v16, v18
	v_add_f32_e32 v18, 1.0, v20
	v_cmp_gt_f32_e32 vcc, s96, v18
	v_sub_f32_e32 v16, v17, v16
	v_max_f32_e32 v17, v19, v19
	v_cndmask_b32_e64 v20, 0, 32, vcc
	v_ldexp_f32 v18, v18, v20
	v_log_f32_e32 v18, v18
	ds_read_u16 v20, v24 offset:8448
	ds_read_u16 v21, v24 offset:8976
	ds_read_u16 v22, v24 offset:9504
	ds_read_u16 v23, v24 offset:10032
	ds_read_u16 v25, v24 offset:10560
	ds_read_u16 v26, v24 offset:11088
	ds_read_u16 v27, v24 offset:11616
	ds_read_u16 v28, v24 offset:12144
	s_waitcnt lgkmcnt(0)
	v_lshlrev_b32_e32 v20, 16, v20
	v_mul_f32_e64 v29, |v20|, s19
	v_mul_f32_e32 v19, 0x3f317217, v18
	v_fma_f32 v19, v18, s97, -v19
	v_fmac_f32_e32 v19, 0x3377d1cf, v18
	v_exp_f32_e32 v29, v29
	v_fmac_f32_e32 v19, 0x3f317217, v18
	v_cmp_lt_f32_e64 s[38:39], |v18|, s15
	v_min_f32_e32 v17, 0, v17
	v_lshlrev_b32_e32 v21, 16, v21
	v_cndmask_b32_e64 v18, v18, v19, s[38:39]
	v_cndmask_b32_e32 v19, 0, v179, vcc
	v_sub_f32_e32 v18, v18, v19
	v_sub_f32_e32 v17, v17, v18
	v_add_f32_e32 v18, 1.0, v29
	v_cmp_gt_f32_e32 vcc, s96, v18
	v_mul_f32_e64 v29, |v21|, s19
	v_exp_f32_e32 v29, v29
	v_cndmask_b32_e64 v19, 0, 32, vcc
	v_ldexp_f32 v18, v18, v19
	v_log_f32_e32 v18, v18
	v_max_f32_e32 v19, v20, v20
	v_min_f32_e32 v19, 0, v19
	v_lshlrev_b32_e32 v22, 16, v22
	v_mul_f32_e32 v20, 0x3f317217, v18
	v_fma_f32 v20, v18, s97, -v20
	v_fmac_f32_e32 v20, 0x3377d1cf, v18
	v_fmac_f32_e32 v20, 0x3f317217, v18
	v_cmp_lt_f32_e64 s[38:39], |v18|, s15
	v_lshlrev_b32_e32 v23, 16, v23
	v_lshlrev_b32_e32 v25, 16, v25
	v_cndmask_b32_e64 v18, v18, v20, s[38:39]
	v_cndmask_b32_e32 v20, 0, v179, vcc
	v_sub_f32_e32 v18, v18, v20
	v_add_f32_e32 v20, 1.0, v29
	v_cmp_gt_f32_e32 vcc, s96, v20
	v_sub_f32_e32 v18, v19, v18
	v_max_f32_e32 v19, v21, v21
	v_cndmask_b32_e64 v29, 0, 32, vcc
	v_ldexp_f32 v20, v20, v29
	v_log_f32_e32 v20, v20
	v_mul_f32_e64 v29, |v22|, s19
	v_exp_f32_e32 v29, v29
	v_min_f32_e32 v19, 0, v19
	v_mul_f32_e32 v21, 0x3f317217, v20
	v_fma_f32 v21, v20, s97, -v21
	v_fmac_f32_e32 v21, 0x3377d1cf, v20
	v_fmac_f32_e32 v21, 0x3f317217, v20
	v_cmp_lt_f32_e64 s[38:39], |v20|, s15
	v_lshlrev_b32_e32 v26, 16, v26
	v_lshlrev_b32_e32 v27, 16, v27
	v_cndmask_b32_e64 v20, v20, v21, s[38:39]
	v_cndmask_b32_e32 v21, 0, v179, vcc
	v_sub_f32_e32 v20, v20, v21
	v_sub_f32_e32 v19, v19, v20
	v_add_f32_e32 v20, 1.0, v29
	v_cmp_gt_f32_e32 vcc, s96, v20
	v_mul_f32_e64 v29, |v23|, s19
	v_exp_f32_e32 v29, v29
	v_cndmask_b32_e64 v21, 0, 32, vcc
	v_ldexp_f32 v20, v20, v21
	v_log_f32_e32 v20, v20
	v_max_f32_e32 v21, v22, v22
	v_min_f32_e32 v21, 0, v21
	v_lshlrev_b32_e32 v28, 16, v28
	v_mul_f32_e32 v22, 0x3f317217, v20
	v_fma_f32 v22, v20, s97, -v22
	v_fmac_f32_e32 v22, 0x3377d1cf, v20
	v_fmac_f32_e32 v22, 0x3f317217, v20
	v_cmp_lt_f32_e64 s[38:39], |v20|, s15
	v_fmamk_f32 v16, v16, 0x3d800000, v15
	v_fmamk_f32 v17, v17, 0x3d800000, v16
	v_cndmask_b32_e64 v20, v20, v22, s[38:39]
	v_cndmask_b32_e32 v22, 0, v179, vcc
	v_sub_f32_e32 v20, v20, v22
	v_add_f32_e32 v22, 1.0, v29
	v_cmp_gt_f32_e32 vcc, s96, v22
	v_sub_f32_e32 v20, v21, v20
	v_max_f32_e32 v21, v23, v23
	v_cndmask_b32_e64 v29, 0, 32, vcc
	v_ldexp_f32 v22, v22, v29
	v_log_f32_e32 v22, v22
	v_mul_f32_e64 v29, |v25|, s19
	v_exp_f32_e32 v29, v29
	v_min_f32_e32 v21, 0, v21
	v_mul_f32_e32 v23, 0x3f317217, v22
	v_fma_f32 v23, v22, s97, -v23
	v_fmac_f32_e32 v23, 0x3377d1cf, v22
	v_fmac_f32_e32 v23, 0x3f317217, v22
	v_cmp_lt_f32_e64 s[38:39], |v22|, s15
	v_fmamk_f32 v18, v18, 0x3d800000, v17
	v_fmamk_f32 v19, v19, 0x3d800000, v18
	v_cndmask_b32_e64 v22, v22, v23, s[38:39]
	v_cndmask_b32_e32 v23, 0, v179, vcc
	v_sub_f32_e32 v22, v22, v23
	v_sub_f32_e32 v21, v21, v22
	v_add_f32_e32 v22, 1.0, v29
	v_cmp_gt_f32_e32 vcc, s96, v22
	v_mul_f32_e64 v29, |v26|, s19
	v_exp_f32_e32 v29, v29
	v_cndmask_b32_e64 v23, 0, 32, vcc
	v_ldexp_f32 v22, v22, v23
	v_log_f32_e32 v22, v22
	v_max_f32_e32 v23, v25, v25
	v_min_f32_e32 v23, 0, v23
	v_fmamk_f32 v20, v20, 0x3d800000, v19
	v_mul_f32_e32 v25, 0x3f317217, v22
	v_fma_f32 v25, v22, s97, -v25
	v_fmac_f32_e32 v25, 0x3377d1cf, v22
	v_fmac_f32_e32 v25, 0x3f317217, v22
	v_cmp_lt_f32_e64 s[38:39], |v22|, s15
	v_fmamk_f32 v21, v21, 0x3d800000, v20
	s_nop 0
	v_cndmask_b32_e64 v22, v22, v25, s[38:39]
	v_cndmask_b32_e32 v25, 0, v179, vcc
	v_sub_f32_e32 v22, v22, v25
	v_add_f32_e32 v25, 1.0, v29
	v_cmp_gt_f32_e32 vcc, s96, v25
	v_sub_f32_e32 v22, v23, v22
	v_max_f32_e32 v23, v26, v26
	v_cndmask_b32_e64 v29, 0, 32, vcc
	v_ldexp_f32 v25, v25, v29
	v_log_f32_e32 v25, v25
	v_mul_f32_e64 v29, |v27|, s19
	v_exp_f32_e32 v29, v29
	v_min_f32_e32 v23, 0, v23
	v_mul_f32_e32 v26, 0x3f317217, v25
	v_fma_f32 v26, v25, s97, -v26
	v_fmac_f32_e32 v26, 0x3377d1cf, v25
	v_fmac_f32_e32 v26, 0x3f317217, v25
	v_cmp_lt_f32_e64 s[38:39], |v25|, s15
	v_fmamk_f32 v22, v22, 0x3d800000, v21
	s_nop 0
	v_cndmask_b32_e64 v25, v25, v26, s[38:39]
	v_cndmask_b32_e32 v26, 0, v179, vcc
	v_sub_f32_e32 v25, v25, v26
	v_sub_f32_e32 v23, v23, v25
	v_add_f32_e32 v25, 1.0, v29
	v_cmp_gt_f32_e32 vcc, s96, v25
	v_mul_f32_e64 v29, |v28|, s19
	v_exp_f32_e32 v29, v29
	v_cndmask_b32_e64 v26, 0, 32, vcc
	v_ldexp_f32 v25, v25, v26
	v_log_f32_e32 v25, v25
	v_max_f32_e32 v26, v27, v27
	v_min_f32_e32 v26, 0, v26
	v_fmamk_f32 v23, v23, 0x3d800000, v22
	v_mul_f32_e32 v27, 0x3f317217, v25
	v_fma_f32 v27, v25, s97, -v27
	v_fmac_f32_e32 v27, 0x3377d1cf, v25
	v_fmac_f32_e32 v27, 0x3f317217, v25
	v_cmp_lt_f32_e64 s[38:39], |v25|, s15
	s_nop 1
	v_cndmask_b32_e64 v25, v25, v27, s[38:39]
	v_cndmask_b32_e32 v27, 0, v179, vcc
	v_sub_f32_e32 v25, v25, v27
	v_add_f32_e32 v27, 1.0, v29
	v_cmp_gt_f32_e32 vcc, s96, v27
	v_sub_f32_e32 v25, v26, v25
	v_max_f32_e32 v26, v28, v28
	v_cndmask_b32_e64 v29, 0, 32, vcc
	v_ldexp_f32 v27, v27, v29
	v_log_f32_e32 v27, v27
	ds_read_u16 v29, v24 offset:12672
	ds_read_u16 v30, v24 offset:13200
	ds_read_u16 v31, v24 offset:13728
	ds_read_u16 v32, v24 offset:14256
	ds_read_u16 v33, v24 offset:14784
	ds_read_u16 v189, v24 offset:15312
	ds_read_u16 v190, v24 offset:15840
	ds_read_u16 v191, v24 offset:16368
	s_waitcnt lgkmcnt(0)
	v_lshlrev_b32_e32 v29, 16, v29
	v_mul_f32_e64 v24, |v29|, s19
	v_mul_f32_e32 v28, 0x3f317217, v27
	v_fma_f32 v28, v27, s97, -v28
	v_fmac_f32_e32 v28, 0x3377d1cf, v27
	v_exp_f32_e32 v192, v24
	v_fmac_f32_e32 v28, 0x3f317217, v27
	v_cmp_lt_f32_e64 s[38:39], |v27|, s15
	v_min_f32_e32 v26, 0, v26
	s_nop 0
	v_cndmask_b32_e64 v27, v27, v28, s[38:39]
	v_cndmask_b32_e32 v28, 0, v179, vcc
	v_sub_f32_e32 v24, v27, v28
	v_sub_f32_e32 v26, v26, v24
	v_fmamk_f32 v24, v25, 0x3d800000, v23
	v_add_f32_e32 v25, 1.0, v192
	v_cmp_gt_f32_e32 vcc, s96, v25
	s_nop 1
	v_cndmask_b32_e64 v27, 0, 32, vcc
	v_ldexp_f32 v25, v25, v27
	v_log_f32_e32 v27, v25
	v_fmamk_f32 v25, v26, 0x3d800000, v24
	v_max_f32_e32 v26, v29, v29
	v_lshlrev_b32_e32 v29, 16, v30
	v_mul_f32_e32 v28, 0x3f317217, v27
	v_mul_f32_e64 v30, |v29|, s19
	v_fma_f32 v28, v27, s97, -v28
	v_exp_f32_e32 v30, v30
	v_fmac_f32_e32 v28, 0x3377d1cf, v27
	v_fmac_f32_e32 v28, 0x3f317217, v27
	v_cmp_lt_f32_e64 s[38:39], |v27|, s15
	v_min_f32_e32 v26, 0, v26
	s_nop 0
	v_cndmask_b32_e64 v27, v27, v28, s[38:39]
	v_cndmask_b32_e32 v28, 0, v179, vcc
	v_sub_f32_e32 v27, v27, v28
	v_add_f32_e32 v28, 1.0, v30
	v_cmp_gt_f32_e32 vcc, s96, v28
	v_sub_f32_e32 v26, v26, v27
	v_max_f32_e32 v27, v29, v29
	v_cndmask_b32_e64 v30, 0, 32, vcc
	v_ldexp_f32 v28, v28, v30
	v_log_f32_e32 v28, v28
	v_lshlrev_b32_e32 v30, 16, v31
	v_mul_f32_e64 v31, |v30|, s19
	v_exp_f32_e32 v31, v31
	v_mul_f32_e32 v29, 0x3f317217, v28
	v_fma_f32 v29, v28, s97, -v29
	v_fmac_f32_e32 v29, 0x3377d1cf, v28
	v_fmac_f32_e32 v29, 0x3f317217, v28
	v_cmp_lt_f32_e64 s[38:39], |v28|, s15
	v_min_f32_e32 v27, 0, v27
	v_fmamk_f32 v26, v26, 0x3d800000, v25
	v_cndmask_b32_e64 v28, v28, v29, s[38:39]
	v_cndmask_b32_e32 v29, 0, v179, vcc
	v_sub_f32_e32 v28, v28, v29
	v_sub_f32_e32 v27, v27, v28
	v_add_f32_e32 v28, 1.0, v31
	v_cmp_gt_f32_e32 vcc, s96, v28
	v_lshlrev_b32_e32 v31, 16, v32
	v_mul_f32_e64 v32, |v31|, s19
	v_cndmask_b32_e64 v29, 0, 32, vcc
	v_ldexp_f32 v28, v28, v29
	v_log_f32_e32 v28, v28
	v_max_f32_e32 v29, v30, v30
	v_exp_f32_e32 v32, v32
	v_min_f32_e32 v29, 0, v29
	v_mul_f32_e32 v30, 0x3f317217, v28
	v_fma_f32 v30, v28, s97, -v30
	v_fmac_f32_e32 v30, 0x3377d1cf, v28
	v_fmac_f32_e32 v30, 0x3f317217, v28
	v_cmp_lt_f32_e64 s[38:39], |v28|, s15
	v_fmamk_f32 v27, v27, 0x3d800000, v26
	s_nop 0
	v_cndmask_b32_e64 v28, v28, v30, s[38:39]
	v_cndmask_b32_e32 v30, 0, v179, vcc
	v_sub_f32_e32 v28, v28, v30
	v_add_f32_e32 v30, 1.0, v32
	v_cmp_gt_f32_e32 vcc, s96, v30
	v_sub_f32_e32 v28, v29, v28
	v_max_f32_e32 v29, v31, v31
	v_cndmask_b32_e64 v32, 0, 32, vcc
	v_ldexp_f32 v30, v30, v32
	v_log_f32_e32 v30, v30
	v_lshlrev_b32_e32 v32, 16, v33
	v_mul_f32_e64 v33, |v32|, s19
	v_exp_f32_e32 v33, v33
	v_mul_f32_e32 v31, 0x3f317217, v30
	v_fma_f32 v31, v30, s97, -v31
	v_fmac_f32_e32 v31, 0x3377d1cf, v30
	v_fmac_f32_e32 v31, 0x3f317217, v30
	v_cmp_lt_f32_e64 s[38:39], |v30|, s15
	v_min_f32_e32 v29, 0, v29
	v_fmamk_f32 v28, v28, 0x3d800000, v27
	v_cndmask_b32_e64 v30, v30, v31, s[38:39]
	v_cndmask_b32_e32 v31, 0, v179, vcc
	v_sub_f32_e32 v30, v30, v31
	v_sub_f32_e32 v29, v29, v30
	v_add_f32_e32 v30, 1.0, v33
	v_cmp_gt_f32_e32 vcc, s96, v30
	v_lshlrev_b32_e32 v33, 16, v189
	v_mul_f32_e64 v189, |v33|, s19
	v_cndmask_b32_e64 v31, 0, 32, vcc
	v_ldexp_f32 v30, v30, v31
	v_log_f32_e32 v30, v30
	v_max_f32_e32 v31, v32, v32
	v_exp_f32_e32 v189, v189
	v_min_f32_e32 v31, 0, v31
	v_mul_f32_e32 v32, 0x3f317217, v30
	v_fma_f32 v32, v30, s97, -v32
	v_fmac_f32_e32 v32, 0x3377d1cf, v30
	v_fmac_f32_e32 v32, 0x3f317217, v30
	v_cmp_lt_f32_e64 s[38:39], |v30|, s15
	v_fmamk_f32 v29, v29, 0x3d800000, v28
	s_nop 0
	v_cndmask_b32_e64 v30, v30, v32, s[38:39]
	v_cndmask_b32_e32 v32, 0, v179, vcc
	v_sub_f32_e32 v30, v30, v32
	v_add_f32_e32 v32, 1.0, v189
	v_cmp_gt_f32_e32 vcc, s96, v32
	v_sub_f32_e32 v30, v31, v30
	v_max_f32_e32 v31, v33, v33
	v_cndmask_b32_e64 v189, 0, 32, vcc
	v_ldexp_f32 v32, v32, v189
	v_log_f32_e32 v32, v32
	v_lshlrev_b32_e32 v189, 16, v190
	v_mul_f32_e64 v190, |v189|, s19
	v_exp_f32_e32 v190, v190
	v_mul_f32_e32 v33, 0x3f317217, v32
	v_fma_f32 v33, v32, s97, -v33
	v_fmac_f32_e32 v33, 0x3377d1cf, v32
	v_fmac_f32_e32 v33, 0x3f317217, v32
	v_cmp_lt_f32_e64 s[38:39], |v32|, s15
	v_min_f32_e32 v31, 0, v31
	v_fmamk_f32 v30, v30, 0x3d800000, v29
	v_cndmask_b32_e64 v32, v32, v33, s[38:39]
	v_cndmask_b32_e32 v33, 0, v179, vcc
	v_sub_f32_e32 v32, v32, v33
	v_sub_f32_e32 v31, v31, v32
	v_add_f32_e32 v32, 1.0, v190
	v_cmp_gt_f32_e32 vcc, s96, v32
	v_lshlrev_b32_e32 v190, 16, v191
	v_mul_f32_e64 v191, |v190|, s19
	v_cndmask_b32_e64 v33, 0, 32, vcc
	v_ldexp_f32 v32, v32, v33
	v_log_f32_e32 v32, v32
	v_max_f32_e32 v33, v189, v189
	v_exp_f32_e32 v191, v191
	v_min_f32_e32 v33, 0, v33
	v_mul_f32_e32 v189, 0x3f317217, v32
	v_fma_f32 v189, v32, s97, -v189
	v_fmac_f32_e32 v189, 0x3377d1cf, v32
	v_fmac_f32_e32 v189, 0x3f317217, v32
	v_cmp_lt_f32_e64 s[38:39], |v32|, s15
	v_fmamk_f32 v31, v31, 0x3d800000, v30
	s_nop 0
	v_cndmask_b32_e64 v32, v32, v189, s[38:39]
	v_cndmask_b32_e32 v189, 0, v179, vcc
	v_sub_f32_e32 v32, v32, v189
	v_add_f32_e32 v189, 1.0, v191
	v_cmp_gt_f32_e32 vcc, s96, v189
	v_sub_f32_e32 v32, v33, v32
	v_max_f32_e32 v33, v190, v190
	v_cndmask_b32_e64 v191, 0, 32, vcc
	v_ldexp_f32 v189, v189, v191
	v_log_f32_e32 v189, v189
	v_min_f32_e32 v33, 0, v33
	v_fmamk_f32 v32, v32, 0x3d800000, v31
	v_mul_f32_e32 v190, 0x3f317217, v189
	v_fma_f32 v190, v189, s97, -v190
	v_fmac_f32_e32 v190, 0x3377d1cf, v189
	v_fmac_f32_e32 v190, 0x3f317217, v189
	v_cmp_lt_f32_e64 s[38:39], |v189|, s15
	s_nop 1
	v_cndmask_b32_e64 v189, v189, v190, s[38:39]
	v_cndmask_b32_e32 v190, 0, v179, vcc
	v_sub_f32_e32 v189, v189, v190
	v_sub_f32_e32 v33, v33, v189
	v_mov_b32_e32 v189, 2
	v_lshlrev_b32_e32 v190, 10, v160
	v_lshlrev_b32_sdwa v189, v189, v109 dst_sel:DWORD dst_unused:UNUSED_PAD src0_sel:DWORD src1_sel:BYTE_0
	v_fmamk_f32 v33, v33, 0x3d800000, v32
	v_add3_u32 v190, v187, v190, v189
	v_cmp_lt_u32_e32 vcc, s2, v109
	ds_write_b32 v190, v33
	s_waitcnt lgkmcnt(0)
	s_barrier
	s_and_saveexec_b64 s[2:3], vcc
	s_cbranch_execz .LBB0_168
	v_add_u32_e32 v187, v187, v189
	ds_read_b32 v190, v187
	s_waitcnt lgkmcnt(0)
	v_pk_add_f32 v[32:33], v[32:33], v[190:191] op_sel_hi:[1,0]
	v_pk_add_f32 v[30:31], v[30:31], v[190:191] op_sel_hi:[1,0]
	v_pk_add_f32 v[28:29], v[28:29], v[190:191] op_sel_hi:[1,0]
	v_pk_add_f32 v[26:27], v[26:27], v[190:191] op_sel_hi:[1,0]
	v_pk_add_f32 v[24:25], v[24:25], v[190:191] op_sel_hi:[1,0]
	v_pk_add_f32 v[22:23], v[22:23], v[190:191] op_sel_hi:[1,0]
	v_pk_add_f32 v[20:21], v[20:21], v[190:191] op_sel_hi:[1,0]
	v_pk_add_f32 v[18:19], v[18:19], v[190:191] op_sel_hi:[1,0]
	v_pk_add_f32 v[16:17], v[16:17], v[190:191] op_sel_hi:[1,0]
	v_pk_add_f32 v[14:15], v[14:15], v[190:191] op_sel_hi:[1,0]
	v_pk_add_f32 v[12:13], v[12:13], v[190:191] op_sel_hi:[1,0]
	v_pk_add_f32 v[10:11], v[10:11], v[190:191] op_sel_hi:[1,0]
	v_pk_add_f32 v[8:9], v[8:9], v[190:191] op_sel_hi:[1,0]
	v_pk_add_f32 v[6:7], v[6:7], v[190:191] op_sel_hi:[1,0]
	v_pk_add_f32 v[4:5], v[4:5], v[190:191] op_sel_hi:[1,0]
	v_pk_add_f32 v[2:3], v[2:3], v[190:191] op_sel_hi:[1,0]

.LBB0_182:
	s_or_b64 exec, exec, s[2:3]
	v_add_co_u32_e32 v8, vcc, 0x6000, v6
	s_mov_b32 s2, 0xc000
	s_nop 0
	v_addc_co_u32_e32 v9, vcc, 0, v7, vcc
	flat_load_ushort v193, v[8:9] offset:2560
	v_add_co_u32_e32 v8, vcc, 0x8000, v6
	v_add_u32_e32 v0, 0x400, v104
	s_nop 0
	v_addc_co_u32_e32 v9, vcc, 0, v7, vcc
	flat_load_ushort v194, v[8:9] offset:2048
	v_add_co_u32_e32 v8, vcc, 0xa000, v6
	s_nop 1
	v_addc_co_u32_e32 v9, vcc, 0, v7, vcc
	flat_load_ushort v190, v[8:9] offset:1536
	v_add_co_u32_e32 v8, vcc, s2, v6
	s_mov_b32 s2, 0x11000
	s_nop 0
	v_addc_co_u32_e32 v9, vcc, 0, v7, vcc
	flat_load_ushort v191, v[8:9] offset:1024
	v_add_co_u32_e32 v8, vcc, 0xe000, v6
	s_nop 1
	v_addc_co_u32_e32 v9, vcc, 0, v7, vcc
	flat_load_ushort v186, v[8:9] offset:512
	v_add_co_u32_e32 v8, vcc, s28, v6
	s_nop 1
	v_addc_co_u32_e32 v9, vcc, 0, v7, vcc
	flat_load_ushort v187, v[8:9]
	v_add_co_u32_e32 v8, vcc, s2, v6
	s_mov_b32 s2, 0x20000
	s_nop 0
	v_addc_co_u32_e32 v9, vcc, 0, v7, vcc
	flat_load_ushort v188, v[8:9] offset:3584
	v_add_co_u32_e32 v8, vcc, 0x13000, v6
	s_nop 1
	v_addc_co_u32_e32 v9, vcc, 0, v7, vcc
	flat_load_ushort v189, v[8:9] offset:3072
	v_add_co_u32_e32 v8, vcc, 0x15000, v6
	s_nop 1
	v_addc_co_u32_e32 v9, vcc, 0, v7, vcc
	flat_load_ushort v168, v[8:9] offset:2560
	v_add_co_u32_e32 v8, vcc, 0x17000, v6
	s_nop 1
	v_addc_co_u32_e32 v9, vcc, 0, v7, vcc
	flat_load_ushort v184, v[8:9] offset:2048
	v_add_co_u32_e32 v8, vcc, 0x19000, v6
	s_nop 1
	v_addc_co_u32_e32 v9, vcc, 0, v7, vcc
	flat_load_ushort v166, v[8:9] offset:1536
	v_add_co_u32_e32 v8, vcc, 0x1b000, v6
	s_nop 1
	v_addc_co_u32_e32 v9, vcc, 0, v7, vcc
	flat_load_ushort v167, v[8:9] offset:1024
	v_add_co_u32_e32 v8, vcc, 0x1d000, v6
	s_nop 1
	v_addc_co_u32_e32 v9, vcc, 0, v7, vcc
	flat_load_ushort v162, v[8:9] offset:512
	v_add_co_u32_e32 v8, vcc, 0x1f000, v6
	s_nop 1
	v_addc_co_u32_e32 v9, vcc, 0, v7, vcc
	flat_load_ushort v163, v[8:9]
	v_add_co_u32_e32 v8, vcc, s2, v6
	s_mov_b32 s2, 0x28000
	s_nop 0
	v_addc_co_u32_e32 v9, vcc, 0, v7, vcc
	flat_load_ushort v164, v[8:9] offset:3584
	v_add_co_u32_e32 v8, vcc, 0x22000, v6
	s_nop 1
	v_addc_co_u32_e32 v9, vcc, 0, v7, vcc
	flat_load_ushort v165, v[8:9] offset:3072
	v_add_co_u32_e32 v8, vcc, 0x24000, v6
	s_nop 1
	v_addc_co_u32_e32 v9, vcc, 0, v7, vcc
	s_nop 0
	flat_load_ushort v159, v[8:9] offset:2560
	v_add_co_u32_e32 v8, vcc, 0x26000, v6
	s_nop 1
	v_addc_co_u32_e32 v9, vcc, 0, v7, vcc
	flat_load_ushort v160, v[8:9] offset:2048
	v_add_co_u32_e32 v8, vcc, s2, v6
	s_mov_b32 s2, 0x2aaaaaab
	s_nop 0
	v_addc_co_u32_e32 v9, vcc, 0, v7, vcc
	flat_load_ushort v157, v[8:9] offset:1536
	v_add_co_u32_e32 v8, vcc, 0x2a000, v6
	s_nop 1
	v_addc_co_u32_e32 v9, vcc, 0, v7, vcc
	flat_load_ushort v158, v[8:9] offset:1024
	v_add_co_u32_e32 v8, vcc, 0x2c000, v6
	s_nop 1
	v_addc_co_u32_e32 v9, vcc, 0, v7, vcc
	flat_load_ushort v153, v[8:9] offset:512
	v_add_co_u32_e32 v8, vcc, 0x2e000, v6
	s_nop 1
	v_addc_co_u32_e32 v9, vcc, 0, v7, vcc
	flat_load_ushort v154, v[8:9]
	v_add_co_u32_e32 v8, vcc, 0x2f000, v6
	s_nop 1
	v_addc_co_u32_e32 v9, vcc, 0, v7, vcc
	flat_load_ushort v155, v[8:9] offset:3584
	v_add_co_u32_e32 v8, vcc, 0x31000, v6
	s_nop 1
	v_addc_co_u32_e32 v9, vcc, 0, v7, vcc
	flat_load_ushort v156, v[8:9] offset:3072
	v_add_co_u32_e32 v8, vcc, 0x33000, v6
	s_nop 1
	v_addc_co_u32_e32 v9, vcc, 0, v7, vcc
	flat_load_ushort v151, v[8:9] offset:2560
	v_add_co_u32_e32 v8, vcc, 0x35000, v6
	s_nop 1
	v_addc_co_u32_e32 v9, vcc, 0, v7, vcc
	flat_load_ushort v152, v[8:9] offset:2048
	v_add_co_u32_e32 v8, vcc, 0x37000, v6
	s_nop 1
	v_addc_co_u32_e32 v9, vcc, 0, v7, vcc
	flat_load_ushort v149, v[8:9] offset:1536
	v_add_co_u32_e32 v8, vcc, 0x39000, v6
	s_nop 1
	v_addc_co_u32_e32 v9, vcc, 0, v7, vcc
	flat_load_ushort v150, v[8:9] offset:1024
	v_add_co_u32_e32 v8, vcc, 0x3b000, v6
	s_nop 1
	v_addc_co_u32_e32 v9, vcc, 0, v7, vcc
	flat_load_ushort v147, v[8:9] offset:512
	v_add_co_u32_e32 v8, vcc, 0x3d000, v6
	s_nop 1
	v_addc_co_u32_e32 v9, vcc, 0, v7, vcc
	flat_load_ushort v148, v[8:9]
	v_add_co_u32_e32 v8, vcc, 0x3e000, v6
	s_nop 1
	v_addc_co_u32_e32 v9, vcc, 0, v7, vcc
	v_add_co_u32_e32 v6, vcc, s29, v6
	flat_load_ushort v143, v[8:9] offset:3584
	s_nop 0
	v_addc_co_u32_e32 v7, vcc, 0, v7, vcc
	flat_load_ushort v144, v[6:7] offset:3072
	v_mul_hi_i32 v6, v0, s2
	v_lshrrev_b32_e32 v7, 31, v6
	v_ashrrev_i32_e32 v6, 6, v6
	v_add_u32_e32 v122, v6, v7
	v_mul_i32_i24_e32 v6, 0x180, v122
	v_sub_u32_e32 v140, v0, v6
	v_lshlrev_b32_e32 v132, 1, v140
	v_and_b32_e32 v130, 0x7f, v140
	v_and_b32_e32 v0, 0xffffff00, v132
	v_lshlrev_b32_e32 v100, 5, v122
	v_or3_b32 v6, s53, v0, v130
	v_add_u32_e32 v0, s58, v100
	v_mov_b64_e32 v[8:9], s[26:27]
	v_mad_i64_i32 v[8:9], s[2:3], v0, s18, v[8:9]
	v_ashrrev_i32_e32 v7, 31, v6
	v_lshl_add_u64 v[22:23], v[6:7], 1, v[8:9]
	v_cmp_lt_i32_e64 s[38:39], s57, v100
	v_mov_b32_e32 v7, 0
	v_mov_b32_e32 v8, 0
	v_mov_b32_e32 v9, 0
	v_mov_b32_e32 v234, 0
	v_mov_b32_e32 v235, 0
	s_and_saveexec_b64 s[2:3], s[38:39]
	s_cbranch_execz .LBB0_184
	v_add_co_u32_e32 v8, vcc, 0x2000, v22
	s_nop 1
	v_addc_co_u32_e32 v9, vcc, 0, v23, vcc
	flat_load_ushort v234, v[8:9] offset:3584
	v_add_co_u32_e32 v8, vcc, 0x1000, v22
	s_nop 1
	v_addc_co_u32_e32 v9, vcc, 0, v23, vcc
	flat_load_ushort v235, v[8:9]
	s_nop 0
	s_nop 0
	s_nop 0

.LBB0_295:
	s_waitcnt vmcnt(0) lgkmcnt(0)
	v_lshlrev_b32_e32 v22, 16, v112
	v_and_b32_e32 v23, 0xffff0000, v112
	v_lshlrev_b32_e32 v18, 16, v113
	v_and_b32_e32 v19, 0xffff0000, v113
	v_pk_mul_f32 v[24:25], v[22:23], v[22:23]
	v_pk_mul_f32 v[20:21], v[18:19], v[18:19]
	v_add_f32_e32 v2, v24, v25
	v_lshlrev_b32_e32 v12, 16, v114
	v_and_b32_e32 v13, 0xffff0000, v114
	v_add_f32_e32 v2, v20, v2
	v_pk_mul_f32 v[14:15], v[12:13], v[12:13]
	v_add_f32_e32 v2, v21, v2
	v_lshlrev_b32_e32 v4, 16, v115
	v_and_b32_e32 v5, 0xffff0000, v115
	v_add_f32_e32 v2, v14, v2
	v_pk_mul_f32 v[10:11], v[4:5], v[4:5]
	v_add_f32_e32 v2, v15, v2
	v_add_f32_e32 v2, v10, v2
	v_add_f32_e32 v2, v11, v2
	s_nop 1
	v_add_f32_dpp v2, v2, v2 quad_perm:[1,0,3,2] row_mask:0xf bank_mask:0xf
	s_nop 1
	v_add_f32_dpp v2, v2, v2 quad_perm:[2,3,0,1] row_mask:0xf bank_mask:0xf
	s_nop 1
	v_add_f32_dpp v2, v2, v2 row_half_mirror row_mask:0xf bank_mask:0xf
	v_fmamk_f32 v2, v2, 0x3c800000, v173
	v_mul_f32_e32 v6, 0x4b800000, v2
	v_cmp_gt_f32_e64 s[42:43], s96, v2
	s_nop 1
	v_cndmask_b32_e64 v2, v2, v6, s[42:43]
	v_rsq_f32_e32 v2, v2
	s_nop 0
	v_mul_f32_e32 v6, 0x45800000, v2
	v_cndmask_b32_e64 v2, v2, v6, s[42:43]
	v_pk_mul_f32 v[10:11], v[2:3], v[22:23] op_sel_hi:[0,1]
	v_pk_mul_f32 v[14:15], v[2:3], v[18:19] op_sel_hi:[0,1]
	v_pk_mul_f32 v[12:13], v[2:3], v[12:13] op_sel_hi:[0,1]
	v_pk_mul_f32 v[4:5], v[2:3], v[4:5] op_sel_hi:[0,1]
	v_pk_mul_f32 v[10:11], v[100:101], v[10:11]
	v_pk_mul_f32 v[14:15], v[102:103], v[14:15]
	v_pk_mul_f32 v[12:13], v[96:97], v[12:13]
	v_pk_mul_f32 v[4:5], v[98:99], v[4:5]
	v_cvt_pk_bf16_f32 v10, v10, v11
	v_cvt_pk_bf16_f32 v11, v14, v15
	v_cvt_pk_bf16_f32 v12, v12, v13
	v_cvt_pk_bf16_f32 v13, v4, v5
	v_mad_u64_u32 v[4:5], s[10:11], v168, s89, v[158:159]
	ds_write_b128 v4, v[10:13] offset:18432

.LBB0_336:
	s_waitcnt vmcnt(0) lgkmcnt(0)
	v_lshlrev_b32_e32 v14, 16, v112
	v_and_b32_e32 v15, 0xffff0000, v112
	v_lshlrev_b32_e32 v10, 16, v113
	v_and_b32_e32 v11, 0xffff0000, v113
	v_pk_mul_f32 v[64:65], v[14:15], v[14:15]
	v_pk_mul_f32 v[12:13], v[10:11], v[10:11]
	v_add_f32_e32 v64, v64, v65
	v_lshlrev_b32_e32 v6, 16, v114
	v_and_b32_e32 v7, 0xffff0000, v114
	v_add_f32_e32 v12, v12, v64
	v_pk_mul_f32 v[8:9], v[6:7], v[6:7]
	v_add_f32_e32 v12, v13, v12
	v_lshlrev_b32_e32 v2, 16, v115
	v_and_b32_e32 v3, 0xffff0000, v115
	v_add_f32_e32 v8, v8, v12
	v_pk_mul_f32 v[4:5], v[2:3], v[2:3]
	v_add_f32_e32 v8, v9, v8
	v_add_f32_e32 v4, v4, v8
	v_add_f32_e32 v4, v5, v4
	s_nop 1
	v_add_f32_dpp v4, v4, v4 quad_perm:[1,0,3,2] row_mask:0xf bank_mask:0xf
	s_nop 1
	v_add_f32_dpp v4, v4, v4 quad_perm:[2,3,0,1] row_mask:0xf bank_mask:0xf
	s_nop 1
	v_add_f32_dpp v4, v4, v4 row_half_mirror row_mask:0xf bank_mask:0xf
	v_fmamk_f32 v4, v4, 0x3c800000, v173
	v_mul_f32_e32 v5, 0x4b800000, v4
	v_cmp_gt_f32_e64 s[38:39], s96, v4
	s_nop 1
	v_cndmask_b32_e64 v4, v4, v5, s[38:39]
	v_rsq_f32_e32 v4, v4
	s_nop 0
	v_mul_f32_e32 v5, 0x45800000, v4
	v_cndmask_b32_e64 v4, v4, v5, s[38:39]
	v_pk_mul_f32 v[8:9], v[4:5], v[14:15] op_sel_hi:[0,1]
	v_pk_mul_f32 v[10:11], v[4:5], v[10:11] op_sel_hi:[0,1]
	v_pk_mul_f32 v[6:7], v[4:5], v[6:7] op_sel_hi:[0,1]
	v_pk_mul_f32 v[2:3], v[4:5], v[2:3] op_sel_hi:[0,1]
	v_pk_mul_f32 v[8:9], v[100:101], v[8:9]
	v_pk_mul_f32 v[10:11], v[102:103], v[10:11]
	v_pk_mul_f32 v[6:7], v[96:97], v[6:7]
	v_pk_mul_f32 v[12:13], v[98:99], v[2:3]
	v_cvt_pk_bf16_f32 v2, v8, v9
	v_cvt_pk_bf16_f32 v3, v10, v11
	v_cvt_pk_bf16_f32 v4, v6, v7
	v_cvt_pk_bf16_f32 v5, v12, v13
	ds_write_b128 v0, v[2:5] offset:18432

.LBB0_342:
	s_waitcnt vmcnt(0) lgkmcnt(0)
	v_lshlrev_b32_e32 v14, 16, v104
	v_and_b32_e32 v15, 0xffff0000, v104
	v_lshlrev_b32_e32 v10, 16, v105
	v_and_b32_e32 v11, 0xffff0000, v105
	v_pk_mul_f32 v[64:65], v[14:15], v[14:15]
	v_pk_mul_f32 v[12:13], v[10:11], v[10:11]
	v_add_f32_e32 v64, v64, v65
	v_lshlrev_b32_e32 v6, 16, v106
	v_and_b32_e32 v7, 0xffff0000, v106
	v_add_f32_e32 v12, v12, v64
	v_pk_mul_f32 v[8:9], v[6:7], v[6:7]
	v_add_f32_e32 v12, v13, v12
	v_lshlrev_b32_e32 v2, 16, v107
	v_and_b32_e32 v3, 0xffff0000, v107
	v_add_f32_e32 v8, v8, v12
	v_pk_mul_f32 v[4:5], v[2:3], v[2:3]
	v_add_f32_e32 v8, v9, v8
	v_add_f32_e32 v4, v4, v8
	v_add_f32_e32 v4, v5, v4
	s_nop 1
	v_add_f32_dpp v4, v4, v4 quad_perm:[1,0,3,2] row_mask:0xf bank_mask:0xf
	s_nop 1
	v_add_f32_dpp v4, v4, v4 quad_perm:[2,3,0,1] row_mask:0xf bank_mask:0xf
	s_nop 1
	v_add_f32_dpp v4, v4, v4 row_half_mirror row_mask:0xf bank_mask:0xf
	v_fmamk_f32 v4, v4, 0x3c800000, v173
	v_mul_f32_e32 v5, 0x4b800000, v4
	v_cmp_gt_f32_e64 s[38:39], s96, v4
	s_nop 1
	v_cndmask_b32_e64 v4, v4, v5, s[38:39]
	v_rsq_f32_e32 v4, v4
	s_nop 0
	v_mul_f32_e32 v5, 0x45800000, v4
	v_cndmask_b32_e64 v4, v4, v5, s[38:39]
	v_pk_mul_f32 v[8:9], v[4:5], v[14:15] op_sel_hi:[0,1]
	v_pk_mul_f32 v[10:11], v[4:5], v[10:11] op_sel_hi:[0,1]
	v_pk_mul_f32 v[6:7], v[4:5], v[6:7] op_sel_hi:[0,1]
	v_pk_mul_f32 v[2:3], v[4:5], v[2:3] op_sel_hi:[0,1]
	v_pk_mul_f32 v[8:9], v[100:101], v[8:9]
	v_pk_mul_f32 v[10:11], v[102:103], v[10:11]
	v_pk_mul_f32 v[6:7], v[96:97], v[6:7]
	v_pk_mul_f32 v[12:13], v[98:99], v[2:3]
	v_cvt_pk_bf16_f32 v2, v8, v9
	v_cvt_pk_bf16_f32 v3, v10, v11
	v_cvt_pk_bf16_f32 v4, v6, v7
	v_cvt_pk_bf16_f32 v5, v12, v13
	ds_write_b128 v0, v[2:5]
	s_or_b64 exec, exec, s[6:7]
	v_cmp_gt_i32_e64 s[38:39], s60, v209
	s_and_saveexec_b64 s[6:7], s[38:39]
	s_cbranch_execz .LBB0_335
.LBB0_343:
	s_waitcnt vmcnt(0) lgkmcnt(0)
	v_lshlrev_b32_e32 v14, 16, v108
	v_and_b32_e32 v15, 0xffff0000, v108
	v_lshlrev_b32_e32 v10, 16, v109
	v_and_b32_e32 v11, 0xffff0000, v109
	v_pk_mul_f32 v[64:65], v[14:15], v[14:15]
	v_pk_mul_f32 v[12:13], v[10:11], v[10:11]
	v_add_f32_e32 v64, v64, v65
	v_lshlrev_b32_e32 v6, 16, v110
	v_and_b32_e32 v7, 0xffff0000, v110
	v_add_f32_e32 v12, v12, v64
	v_pk_mul_f32 v[8:9], v[6:7], v[6:7]
	v_add_f32_e32 v12, v13, v12
	v_lshlrev_b32_e32 v2, 16, v111
	v_and_b32_e32 v3, 0xffff0000, v111
	v_add_f32_e32 v8, v8, v12
	v_pk_mul_f32 v[4:5], v[2:3], v[2:3]
	v_add_f32_e32 v8, v9, v8
	v_add_f32_e32 v4, v4, v8
	v_add_f32_e32 v4, v5, v4
	s_nop 1
	v_add_f32_dpp v4, v4, v4 quad_perm:[1,0,3,2] row_mask:0xf bank_mask:0xf
	s_nop 1
	v_add_f32_dpp v4, v4, v4 quad_perm:[2,3,0,1] row_mask:0xf bank_mask:0xf
	s_nop 1
	v_add_f32_dpp v4, v4, v4 row_half_mirror row_mask:0xf bank_mask:0xf
	v_fmamk_f32 v4, v4, 0x3c800000, v173
	v_mul_f32_e32 v5, 0x4b800000, v4
	v_cmp_gt_f32_e64 s[38:39], s96, v4
	s_nop 1
	v_cndmask_b32_e64 v4, v4, v5, s[38:39]
	v_rsq_f32_e32 v4, v4
	s_nop 0
	v_mul_f32_e32 v5, 0x45800000, v4
	v_cndmask_b32_e64 v4, v4, v5, s[38:39]
	v_pk_mul_f32 v[8:9], v[4:5], v[14:15] op_sel_hi:[0,1]
	v_pk_mul_f32 v[10:11], v[4:5], v[10:11] op_sel_hi:[0,1]
	v_pk_mul_f32 v[6:7], v[4:5], v[6:7] op_sel_hi:[0,1]
	v_pk_mul_f32 v[2:3], v[4:5], v[2:3] op_sel_hi:[0,1]
	v_pk_mul_f32 v[8:9], v[100:101], v[8:9]
	v_pk_mul_f32 v[10:11], v[102:103], v[10:11]
	v_pk_mul_f32 v[6:7], v[96:97], v[6:7]
	v_pk_mul_f32 v[12:13], v[98:99], v[2:3]
	v_cvt_pk_bf16_f32 v2, v8, v9
	v_cvt_pk_bf16_f32 v3, v10, v11
	v_cvt_pk_bf16_f32 v4, v6, v7
	v_cvt_pk_bf16_f32 v5, v12, v13
	ds_write_b128 v0, v[2:5] offset:9216
	s_or_b64 exec, exec, s[6:7]
	v_cmp_ge_i32_e64 s[38:39], s62, v209
	s_and_saveexec_b64 s[6:7], s[38:39]
	s_cbranch_execnz .LBB0_336
	s_branch .LBB0_337

.LBB0_348:
	s_waitcnt vmcnt(0) lgkmcnt(0)
	v_lshlrev_b32_e32 v22, 16, v104
	v_and_b32_e32 v23, 0xffff0000, v104
	v_lshlrev_b32_e32 v18, 16, v105
	v_and_b32_e32 v19, 0xffff0000, v105
	v_pk_mul_f32 v[24:25], v[22:23], v[22:23]
	v_pk_mul_f32 v[20:21], v[18:19], v[18:19]
	v_add_f32_e32 v2, v24, v25
	v_lshlrev_b32_e32 v12, 16, v106
	v_and_b32_e32 v13, 0xffff0000, v106
	v_add_f32_e32 v2, v20, v2
	v_pk_mul_f32 v[14:15], v[12:13], v[12:13]
	v_add_f32_e32 v2, v21, v2
	v_lshlrev_b32_e32 v4, 16, v107
	v_and_b32_e32 v5, 0xffff0000, v107
	v_add_f32_e32 v2, v14, v2
	v_pk_mul_f32 v[10:11], v[4:5], v[4:5]
	v_add_f32_e32 v2, v15, v2
	v_add_f32_e32 v2, v10, v2
	v_add_f32_e32 v2, v11, v2
	s_nop 1
	v_add_f32_dpp v2, v2, v2 quad_perm:[1,0,3,2] row_mask:0xf bank_mask:0xf
	s_nop 1
	v_add_f32_dpp v2, v2, v2 quad_perm:[2,3,0,1] row_mask:0xf bank_mask:0xf
	s_nop 1
	v_add_f32_dpp v2, v2, v2 row_half_mirror row_mask:0xf bank_mask:0xf
	v_fmamk_f32 v2, v2, 0x3c800000, v173
	v_mul_f32_e32 v6, 0x4b800000, v2
	v_cmp_gt_f32_e64 s[46:47], s96, v2
	s_nop 1
	v_cndmask_b32_e64 v2, v2, v6, s[46:47]
	v_rsq_f32_e32 v2, v2
	s_nop 0
	v_mul_f32_e32 v6, 0x45800000, v2
	v_cndmask_b32_e64 v2, v2, v6, s[46:47]
	v_pk_mul_f32 v[10:11], v[2:3], v[22:23] op_sel_hi:[0,1]
	v_pk_mul_f32 v[14:15], v[2:3], v[18:19] op_sel_hi:[0,1]
	v_pk_mul_f32 v[12:13], v[2:3], v[12:13] op_sel_hi:[0,1]
	v_pk_mul_f32 v[4:5], v[2:3], v[4:5] op_sel_hi:[0,1]
	v_pk_mul_f32 v[10:11], v[100:101], v[10:11]
	v_pk_mul_f32 v[14:15], v[102:103], v[14:15]
	v_pk_mul_f32 v[12:13], v[96:97], v[12:13]
	v_pk_mul_f32 v[4:5], v[98:99], v[4:5]
	v_cvt_pk_bf16_f32 v10, v10, v11
	v_cvt_pk_bf16_f32 v11, v14, v15
	v_cvt_pk_bf16_f32 v12, v12, v13
	v_cvt_pk_bf16_f32 v13, v4, v5
	v_mad_u64_u32 v[4:5], s[10:11], v168, s89, v[158:159]
	ds_write_b128 v4, v[10:13]
	s_or_b64 exec, exec, s[2:3]
	s_and_saveexec_b64 s[2:3], s[44:45]
	s_cbranch_execz .LBB0_294
.LBB0_349:
	s_waitcnt vmcnt(0) lgkmcnt(0)
	v_lshlrev_b32_e32 v22, 16, v108
	v_and_b32_e32 v23, 0xffff0000, v108
	v_lshlrev_b32_e32 v18, 16, v109
	v_and_b32_e32 v19, 0xffff0000, v109
	v_pk_mul_f32 v[24:25], v[22:23], v[22:23]
	v_pk_mul_f32 v[20:21], v[18:19], v[18:19]
	v_add_f32_e32 v2, v24, v25
	v_lshlrev_b32_e32 v12, 16, v110
	v_and_b32_e32 v13, 0xffff0000, v110
	v_add_f32_e32 v2, v20, v2
	v_pk_mul_f32 v[14:15], v[12:13], v[12:13]
	v_add_f32_e32 v2, v21, v2
	v_lshlrev_b32_e32 v4, 16, v111
	v_and_b32_e32 v5, 0xffff0000, v111
	v_add_f32_e32 v2, v14, v2
	v_pk_mul_f32 v[10:11], v[4:5], v[4:5]
	v_add_f32_e32 v2, v15, v2
	v_add_f32_e32 v2, v10, v2
	v_add_f32_e32 v2, v11, v2
	s_nop 1
	v_add_f32_dpp v2, v2, v2 quad_perm:[1,0,3,2] row_mask:0xf bank_mask:0xf
	s_nop 1
	v_add_f32_dpp v2, v2, v2 quad_perm:[2,3,0,1] row_mask:0xf bank_mask:0xf
	s_nop 1
	v_add_f32_dpp v2, v2, v2 row_half_mirror row_mask:0xf bank_mask:0xf
	v_fmamk_f32 v2, v2, 0x3c800000, v173
	v_mul_f32_e32 v6, 0x4b800000, v2
	v_cmp_gt_f32_e64 s[44:45], s96, v2
	s_nop 1
	v_cndmask_b32_e64 v2, v2, v6, s[44:45]
	v_rsq_f32_e32 v2, v2
	s_nop 0
	v_mul_f32_e32 v6, 0x45800000, v2
	v_cndmask_b32_e64 v2, v2, v6, s[44:45]
	v_pk_mul_f32 v[10:11], v[2:3], v[22:23] op_sel_hi:[0,1]
	v_pk_mul_f32 v[14:15], v[2:3], v[18:19] op_sel_hi:[0,1]
	v_pk_mul_f32 v[12:13], v[2:3], v[12:13] op_sel_hi:[0,1]
	v_pk_mul_f32 v[4:5], v[2:3], v[4:5] op_sel_hi:[0,1]
	v_pk_mul_f32 v[10:11], v[100:101], v[10:11]
	v_pk_mul_f32 v[14:15], v[102:103], v[14:15]
	v_pk_mul_f32 v[12:13], v[96:97], v[12:13]
	v_pk_mul_f32 v[4:5], v[98:99], v[4:5]
	v_cvt_pk_bf16_f32 v10, v10, v11
	v_cvt_pk_bf16_f32 v11, v14, v15
	v_cvt_pk_bf16_f32 v12, v12, v13
	v_cvt_pk_bf16_f32 v13, v4, v5
	v_mad_u64_u32 v[4:5], s[10:11], v168, s89, v[158:159]
	ds_write_b128 v4, v[10:13] offset:9216
	s_or_b64 exec, exec, s[2:3]
	s_and_saveexec_b64 s[2:3], s[42:43]
	s_cbranch_execnz .LBB0_295
	s_branch .LBB0_296
